# GEMM accumulator zero fill moved from tile header into first K-iteration load segments (3 GEMM instantiations)
# baseline (speedup 1.0000x reference)
.LBB0_287:
	s_ashr_i32 s21, s20, 31
	s_lshl_b64 s[22:23], s[20:21], 19
	s_add_u32 s22, s80, s22
	s_addc_u32 s23, s81, s23
	s_and_b64 s[24:25], s[6:7], exec
	s_cselect_b32 s21, s23, s29
	s_cselect_b32 s36, s22, s28
	s_ashr_i32 s19, s18, 31
	s_lshl_b64 s[24:25], s[18:19], 19
	s_add_u32 s24, s40, s24
	s_addc_u32 s25, s41, s25
	s_and_b64 s[34:35], s[6:7], exec
	s_cselect_b32 s19, s25, s31
	s_cselect_b32 s37, s24, s30
	s_add_u32 s38, s30, 0x100
	s_addc_u32 s39, s31, 0
	s_add_u32 s28, s28, 0x40080
	s_addc_u32 s29, s29, 0
	s_mov_b32 s55, -2
.LBB0_288:
	s_add_u32 s30, s28, 0xfffc0080
	s_addc_u32 s31, s29, -1
	s_add_i32 s56, 0, 0x10000
	s_cmp_eq_u32 s55, 12
	s_cselect_b32 s35, s21, s31
	s_cselect_b32 s34, s36, s30
	s_cselect_b32 s31, s19, s39
	s_cselect_b32 s30, s37, s38
	s_add_i32 s58, 0, 0x14000
	v_add_u32_e32 v166, s56, v147
	v_add_u32_e32 v182, s58, v147
	ds_read_b128 v[142:145], v166
	ds_read_b128 v[158:161], v166 offset:1024
	ds_read_b128 v[162:165], v166 offset:2048
	ds_read_b128 v[166:169], v166 offset:3072
	ds_read_b128 v[170:173], v182
	ds_read_b128 v[174:177], v182 offset:1024
	ds_read_b128 v[178:181], v182 offset:2048
	ds_read_b128 v[182:185], v182 offset:3072
	v_lshl_add_u64 v[224:225], s[28:29], 0, v[140:141]
	s_add_i32 m0, s44, 0xc000
	ds_read_b128 v[186:189], v157
	ds_read_b128 v[190:193], v157 offset:1024
	ds_read_b128 v[194:197], v157 offset:2048
	ds_read_b128 v[198:201], v157 offset:3072
	ds_read_b128 v[202:205], v157 offset:4096
	ds_read_b128 v[206:209], v157 offset:5120
	ds_read_b128 v[220:223], v157 offset:6144
	ds_read_b128 v[236:239], v157 offset:7168
	global_load_lds_dwordx4 v[224:225], off
	v_lshl_add_u64 v[224:225], s[28:29], 0, v[138:139]
	s_add_i32 m0, s44, 0xe000
	s_nop 0
	global_load_lds_dwordx4 v[224:225], off
	s_cmp_lg_u32 s55, -2
	s_cbranch_scc1 .Lzf1_0
	v_mov_b32_e32 v66, 0
	v_mov_b32_e32 v67, 0
	v_mov_b32_e32 v68, 0
	v_mov_b32_e32 v69, 0
	v_mov_b32_e32 v70, 0
	v_mov_b32_e32 v71, 0
	v_mov_b32_e32 v72, 0
	v_mov_b32_e32 v73, 0
	v_mov_b32_e32 v74, 0
	v_mov_b32_e32 v75, 0
	v_mov_b32_e32 v76, 0
	v_mov_b32_e32 v77, 0
	v_mov_b32_e32 v78, 0
	v_mov_b32_e32 v79, 0
	v_mov_b32_e32 v80, 0
	v_mov_b32_e32 v81, 0
	v_mov_b32_e32 v82, 0
	v_mov_b32_e32 v83, 0
	v_mov_b32_e32 v84, 0
	v_mov_b32_e32 v85, 0
	v_mov_b32_e32 v86, 0
	v_mov_b32_e32 v87, 0
	v_mov_b32_e32 v88, 0
	v_mov_b32_e32 v89, 0
	v_mov_b32_e32 v90, 0
	v_mov_b32_e32 v91, 0
	v_mov_b32_e32 v92, 0
	v_mov_b32_e32 v93, 0
	v_mov_b32_e32 v94, 0
	v_mov_b32_e32 v95, 0
	v_mov_b32_e32 v96, 0
	v_mov_b32_e32 v97, 0
	v_mov_b32_e32 v98, 0
	v_mov_b32_e32 v99, 0
	v_mov_b32_e32 v100, 0
	v_mov_b32_e32 v101, 0
	v_mov_b32_e32 v102, 0
	v_mov_b32_e32 v103, 0
	v_mov_b32_e32 v104, 0
	v_mov_b32_e32 v105, 0
	v_mov_b32_e32 v106, 0
	v_mov_b32_e32 v107, 0
	v_mov_b32_e32 v108, 0
	v_mov_b32_e32 v109, 0
	v_mov_b32_e32 v110, 0
	v_mov_b32_e32 v111, 0
	v_mov_b32_e32 v112, 0
	v_mov_b32_e32 v113, 0
	v_mov_b32_e32 v114, 0
	v_mov_b32_e32 v115, 0
	v_mov_b32_e32 v116, 0
	v_mov_b32_e32 v117, 0
	v_mov_b32_e32 v118, 0
	v_mov_b32_e32 v119, 0
	v_mov_b32_e32 v120, 0
	v_mov_b32_e32 v121, 0
	v_mov_b32_e32 v122, 0
	v_mov_b32_e32 v123, 0
	v_mov_b32_e32 v124, 0
	v_mov_b32_e32 v125, 0
	v_mov_b32_e32 v126, 0
	v_mov_b32_e32 v127, 0
	v_mov_b32_e32 v128, 0
	v_mov_b32_e32 v129, 0
.Lzf1_0:
	s_waitcnt vmcnt(8)
	s_waitcnt lgkmcnt(0)
	s_barrier
	s_setprio 1
	s_waitcnt lgkmcnt(0)
	v_mfma_f32_16x16x32_bf16 v[126:129], v[142:145], v[186:189], v[126:129]
	v_mfma_f32_16x16x32_bf16 v[122:125], v[162:165], v[186:189], v[122:125]
	v_mfma_f32_16x16x32_bf16 v[110:113], v[142:145], v[194:197], v[110:113]
	v_mfma_f32_16x16x32_bf16 v[106:109], v[162:165], v[194:197], v[106:109]
	v_mfma_f32_16x16x32_bf16 v[94:97], v[142:145], v[202:205], v[94:97]
	v_mfma_f32_16x16x32_bf16 v[90:93], v[162:165], v[202:205], v[90:93]
	v_mfma_f32_16x16x32_bf16 v[78:81], v[142:145], v[220:223], v[78:81]
	v_mfma_f32_16x16x32_bf16 v[74:77], v[162:165], v[220:223], v[74:77]
	v_mfma_f32_16x16x32_bf16 v[126:129], v[158:161], v[190:193], v[126:129]
	v_mfma_f32_16x16x32_bf16 v[122:125], v[166:169], v[190:193], v[122:125]
	v_mfma_f32_16x16x32_bf16 v[110:113], v[158:161], v[198:201], v[110:113]
	v_mfma_f32_16x16x32_bf16 v[106:109], v[166:169], v[198:201], v[106:109]
	v_mfma_f32_16x16x32_bf16 v[94:97], v[158:161], v[206:209], v[94:97]
	v_mfma_f32_16x16x32_bf16 v[90:93], v[166:169], v[206:209], v[90:93]
	v_mfma_f32_16x16x32_bf16 v[78:81], v[158:161], v[236:239], v[78:81]
	v_mfma_f32_16x16x32_bf16 v[74:77], v[166:169], v[236:239], v[74:77]
	s_setprio 0
	s_setprio 1
	v_mfma_f32_16x16x32_bf16 v[118:121], v[170:173], v[186:189], v[118:121]
	v_mfma_f32_16x16x32_bf16 v[114:117], v[178:181], v[186:189], v[114:117]
	v_mfma_f32_16x16x32_bf16 v[102:105], v[170:173], v[194:197], v[102:105]
	v_mfma_f32_16x16x32_bf16 v[98:101], v[178:181], v[194:197], v[98:101]
	v_mfma_f32_16x16x32_bf16 v[86:89], v[170:173], v[202:205], v[86:89]
	v_mfma_f32_16x16x32_bf16 v[82:85], v[178:181], v[202:205], v[82:85]
	v_mfma_f32_16x16x32_bf16 v[70:73], v[170:173], v[220:223], v[70:73]
	v_mfma_f32_16x16x32_bf16 v[66:69], v[178:181], v[220:223], v[66:69]
	v_mfma_f32_16x16x32_bf16 v[118:121], v[174:177], v[190:193], v[118:121]
	v_mfma_f32_16x16x32_bf16 v[114:117], v[182:185], v[190:193], v[114:117]
	v_mfma_f32_16x16x32_bf16 v[102:105], v[174:177], v[198:201], v[102:105]
	v_mfma_f32_16x16x32_bf16 v[98:101], v[182:185], v[198:201], v[98:101]
	v_mfma_f32_16x16x32_bf16 v[86:89], v[174:177], v[206:209], v[86:89]
	v_mfma_f32_16x16x32_bf16 v[82:85], v[182:185], v[206:209], v[82:85]
	v_mfma_f32_16x16x32_bf16 v[70:73], v[174:177], v[236:239], v[70:73]
	v_mfma_f32_16x16x32_bf16 v[66:69], v[182:185], v[236:239], v[66:69]
	s_setprio 0
	s_barrier
	s_add_i32 s56, s56, s27
	v_lshl_add_u64 v[224:225], s[30:31], 0, v[132:133]
	s_mov_b32 m0, s56
	ds_read_b128 v[186:189], v157 offset:16384
	ds_read_b128 v[190:193], v157 offset:17408
	ds_read_b128 v[194:197], v157 offset:18432
	ds_read_b128 v[198:201], v157 offset:19456
	ds_read_b128 v[202:205], v157 offset:20480
	ds_read_b128 v[206:209], v157 offset:21504
	ds_read_b128 v[220:223], v157 offset:22528
	ds_read_b128 v[236:239], v157 offset:23552
	global_load_lds_dwordx4 v[224:225], off
	s_add_i32 m0, s56, 0x2000
	s_add_u32 s56, s30, 0x40000
	v_lshl_add_u64 v[230:231], s[30:31], 0, v[136:137]
	s_addc_u32 s57, s31, 0
	s_add_i32 s58, s58, s27
	global_load_lds_dwordx4 v[230:231], off
	v_lshl_add_u64 v[240:241], s[56:57], 0, v[132:133]
	s_mov_b32 m0, s58
	v_lshl_add_u64 v[242:243], s[34:35], 0, v[134:135]
	global_load_lds_dwordx4 v[240:241], off
	v_lshl_add_u64 v[240:241], s[56:57], 0, v[136:137]
	s_add_i32 m0, s58, 0x2000
	s_nop 0
	global_load_lds_dwordx4 v[240:241], off
	v_lshl_add_u64 v[240:241], s[34:35], 0, v[130:131]
	s_mov_b32 m0, s44
	s_nop 0
	global_load_lds_dwordx4 v[240:241], off
	s_mov_b32 m0, s45
	s_nop 0
	global_load_lds_dwordx4 v[242:243], off
	s_cmp_lg_u32 s55, -2
	s_cbranch_scc1 .Lzf1_1
	v_mov_b32_e32 v2, 0
	v_mov_b32_e32 v3, 0
	v_mov_b32_e32 v4, 0
	v_mov_b32_e32 v5, 0
	v_mov_b32_e32 v6, 0
	v_mov_b32_e32 v7, 0
	v_mov_b32_e32 v8, 0
	v_mov_b32_e32 v9, 0
	v_mov_b32_e32 v10, 0
	v_mov_b32_e32 v11, 0
	v_mov_b32_e32 v12, 0
	v_mov_b32_e32 v13, 0
	v_mov_b32_e32 v14, 0
	v_mov_b32_e32 v15, 0
	v_mov_b32_e32 v16, 0
	v_mov_b32_e32 v17, 0
	v_mov_b32_e32 v18, 0
	v_mov_b32_e32 v19, 0
	v_mov_b32_e32 v20, 0
	v_mov_b32_e32 v21, 0
	v_mov_b32_e32 v22, 0
	v_mov_b32_e32 v23, 0
	v_mov_b32_e32 v24, 0
	v_mov_b32_e32 v25, 0
	v_mov_b32_e32 v26, 0
	v_mov_b32_e32 v27, 0
	v_mov_b32_e32 v28, 0
	v_mov_b32_e32 v29, 0
	v_mov_b32_e32 v30, 0
	v_mov_b32_e32 v31, 0
	v_mov_b32_e32 v32, 0
	v_mov_b32_e32 v33, 0
	v_mov_b32_e32 v34, 0
	v_mov_b32_e32 v35, 0
	v_mov_b32_e32 v36, 0
	v_mov_b32_e32 v37, 0
	v_mov_b32_e32 v38, 0
	v_mov_b32_e32 v39, 0
	v_mov_b32_e32 v40, 0
	v_mov_b32_e32 v41, 0
	v_mov_b32_e32 v42, 0
	v_mov_b32_e32 v43, 0
	v_mov_b32_e32 v44, 0
	v_mov_b32_e32 v45, 0
	v_mov_b32_e32 v46, 0
	v_mov_b32_e32 v47, 0
	v_mov_b32_e32 v48, 0
	v_mov_b32_e32 v49, 0
	v_mov_b32_e32 v50, 0
	v_mov_b32_e32 v51, 0
	v_mov_b32_e32 v52, 0
	v_mov_b32_e32 v53, 0
	v_mov_b32_e32 v54, 0
	v_mov_b32_e32 v55, 0
	v_mov_b32_e32 v56, 0
	v_mov_b32_e32 v57, 0
	v_mov_b32_e32 v58, 0
	v_mov_b32_e32 v59, 0
	v_mov_b32_e32 v60, 0
	v_mov_b32_e32 v61, 0
	v_mov_b32_e32 v62, 0
	v_mov_b32_e32 v63, 0
	v_mov_b32_e32 v64, 0
	v_mov_b32_e32 v65, 0
.Lzf1_1:
	s_waitcnt vmcnt(8)
	s_waitcnt lgkmcnt(0)
	s_barrier
	s_setprio 1
	s_waitcnt lgkmcnt(0)
	v_mfma_f32_16x16x32_bf16 v[62:65], v[142:145], v[186:189], v[62:65]
	v_mfma_f32_16x16x32_bf16 v[58:61], v[162:165], v[186:189], v[58:61]
	v_mfma_f32_16x16x32_bf16 v[46:49], v[142:145], v[194:197], v[46:49]
	v_mfma_f32_16x16x32_bf16 v[42:45], v[162:165], v[194:197], v[42:45]
	v_mfma_f32_16x16x32_bf16 v[30:33], v[142:145], v[202:205], v[30:33]
	v_mfma_f32_16x16x32_bf16 v[26:29], v[162:165], v[202:205], v[26:29]
	v_mfma_f32_16x16x32_bf16 v[14:17], v[142:145], v[220:223], v[14:17]
	v_mfma_f32_16x16x32_bf16 v[10:13], v[162:165], v[220:223], v[10:13]
	v_mfma_f32_16x16x32_bf16 v[62:65], v[158:161], v[190:193], v[62:65]
	v_mfma_f32_16x16x32_bf16 v[58:61], v[166:169], v[190:193], v[58:61]
	v_mfma_f32_16x16x32_bf16 v[46:49], v[158:161], v[198:201], v[46:49]
	v_mfma_f32_16x16x32_bf16 v[42:45], v[166:169], v[198:201], v[42:45]
	v_mfma_f32_16x16x32_bf16 v[30:33], v[158:161], v[206:209], v[30:33]
	v_mfma_f32_16x16x32_bf16 v[26:29], v[166:169], v[206:209], v[26:29]
	v_mfma_f32_16x16x32_bf16 v[14:17], v[158:161], v[236:239], v[14:17]
	v_mfma_f32_16x16x32_bf16 v[10:13], v[166:169], v[236:239], v[10:13]
	s_setprio 0
	s_setprio 1
	v_mfma_f32_16x16x32_bf16 v[54:57], v[170:173], v[186:189], v[54:57]
	v_mfma_f32_16x16x32_bf16 v[50:53], v[178:181], v[186:189], v[50:53]
	v_mfma_f32_16x16x32_bf16 v[38:41], v[170:173], v[194:197], v[38:41]
	v_mfma_f32_16x16x32_bf16 v[34:37], v[178:181], v[194:197], v[34:37]
	v_mfma_f32_16x16x32_bf16 v[22:25], v[170:173], v[202:205], v[22:25]
	v_mfma_f32_16x16x32_bf16 v[18:21], v[178:181], v[202:205], v[18:21]
	v_mfma_f32_16x16x32_bf16 v[6:9], v[170:173], v[220:223], v[6:9]
	v_mfma_f32_16x16x32_bf16 v[2:5], v[178:181], v[220:223], v[2:5]
	v_mfma_f32_16x16x32_bf16 v[54:57], v[174:177], v[190:193], v[54:57]
	v_mfma_f32_16x16x32_bf16 v[50:53], v[182:185], v[190:193], v[50:53]
	v_mfma_f32_16x16x32_bf16 v[38:41], v[174:177], v[198:201], v[38:41]
	v_mfma_f32_16x16x32_bf16 v[34:37], v[182:185], v[198:201], v[34:37]
	v_mfma_f32_16x16x32_bf16 v[22:25], v[174:177], v[206:209], v[22:25]
	v_mfma_f32_16x16x32_bf16 v[18:21], v[182:185], v[206:209], v[18:21]
	v_mfma_f32_16x16x32_bf16 v[6:9], v[174:177], v[236:239], v[6:9]
	v_mfma_f32_16x16x32_bf16 v[2:5], v[182:185], v[236:239], v[2:5]
	s_setprio 0
	s_barrier
	s_add_i32 s56, 0, 0x18000
	s_add_i32 s57, 0, 0x1c000
	v_add_u32_e32 v166, s56, v147
	v_add_u32_e32 v182, s57, v147
	ds_read_b128 v[142:145], v166
	ds_read_b128 v[158:161], v166 offset:1024
	ds_read_b128 v[162:165], v166 offset:2048
	ds_read_b128 v[166:169], v166 offset:3072
	ds_read_b128 v[170:173], v182
	ds_read_b128 v[174:177], v182 offset:1024
	ds_read_b128 v[178:181], v182 offset:2048
	ds_read_b128 v[182:185], v182 offset:3072
	s_add_u32 s34, s34, 0x40000
	s_addc_u32 s35, s35, 0
	s_mov_b32 m0, s43
	v_lshl_add_u64 v[244:245], s[34:35], 0, v[130:131]
	ds_read_b128 v[186:189], v157 offset:32768
	ds_read_b128 v[190:193], v157 offset:33792
	ds_read_b128 v[194:197], v157 offset:34816
	ds_read_b128 v[198:201], v157 offset:35840
	ds_read_b128 v[202:205], v157 offset:36864
	ds_read_b128 v[206:209], v157 offset:37888
	ds_read_b128 v[220:223], v157 offset:38912
	ds_read_b128 v[236:239], v157 offset:39936
	global_load_lds_dwordx4 v[244:245], off
	v_lshl_add_u64 v[244:245], s[34:35], 0, v[134:135]
	s_mov_b32 m0, s46
	s_nop 0
	global_load_lds_dwordx4 v[244:245], off
	s_waitcnt vmcnt(8)
	s_waitcnt lgkmcnt(0)
	s_barrier
	s_setprio 1
	s_waitcnt lgkmcnt(0)
	v_mfma_f32_16x16x32_bf16 v[126:129], v[142:145], v[186:189], v[126:129]
	v_mfma_f32_16x16x32_bf16 v[122:125], v[162:165], v[186:189], v[122:125]
	v_mfma_f32_16x16x32_bf16 v[110:113], v[142:145], v[194:197], v[110:113]
	v_mfma_f32_16x16x32_bf16 v[106:109], v[162:165], v[194:197], v[106:109]
	v_mfma_f32_16x16x32_bf16 v[94:97], v[142:145], v[202:205], v[94:97]
	v_mfma_f32_16x16x32_bf16 v[90:93], v[162:165], v[202:205], v[90:93]
	v_mfma_f32_16x16x32_bf16 v[78:81], v[142:145], v[220:223], v[78:81]
	v_mfma_f32_16x16x32_bf16 v[74:77], v[162:165], v[220:223], v[74:77]
	v_mfma_f32_16x16x32_bf16 v[126:129], v[158:161], v[190:193], v[126:129]
	v_mfma_f32_16x16x32_bf16 v[122:125], v[166:169], v[190:193], v[122:125]
	v_mfma_f32_16x16x32_bf16 v[110:113], v[158:161], v[198:201], v[110:113]
	v_mfma_f32_16x16x32_bf16 v[106:109], v[166:169], v[198:201], v[106:109]
	v_mfma_f32_16x16x32_bf16 v[94:97], v[158:161], v[206:209], v[94:97]
	v_mfma_f32_16x16x32_bf16 v[90:93], v[166:169], v[206:209], v[90:93]
	v_mfma_f32_16x16x32_bf16 v[78:81], v[158:161], v[236:239], v[78:81]
	v_mfma_f32_16x16x32_bf16 v[74:77], v[166:169], v[236:239], v[74:77]
	s_setprio 0
	s_setprio 1
	v_mfma_f32_16x16x32_bf16 v[118:121], v[170:173], v[186:189], v[118:121]
	v_mfma_f32_16x16x32_bf16 v[114:117], v[178:181], v[186:189], v[114:117]
	v_mfma_f32_16x16x32_bf16 v[102:105], v[170:173], v[194:197], v[102:105]
	v_mfma_f32_16x16x32_bf16 v[98:101], v[178:181], v[194:197], v[98:101]
	v_mfma_f32_16x16x32_bf16 v[86:89], v[170:173], v[202:205], v[86:89]
	v_mfma_f32_16x16x32_bf16 v[82:85], v[178:181], v[202:205], v[82:85]
	v_mfma_f32_16x16x32_bf16 v[70:73], v[170:173], v[220:223], v[70:73]
	v_mfma_f32_16x16x32_bf16 v[66:69], v[178:181], v[220:223], v[66:69]
	v_mfma_f32_16x16x32_bf16 v[118:121], v[174:177], v[190:193], v[118:121]
	v_mfma_f32_16x16x32_bf16 v[114:117], v[182:185], v[190:193], v[114:117]
	v_mfma_f32_16x16x32_bf16 v[102:105], v[174:177], v[198:201], v[102:105]
	v_mfma_f32_16x16x32_bf16 v[98:101], v[182:185], v[198:201], v[98:101]
	v_mfma_f32_16x16x32_bf16 v[86:89], v[174:177], v[206:209], v[86:89]
	v_mfma_f32_16x16x32_bf16 v[82:85], v[182:185], v[206:209], v[82:85]
	v_mfma_f32_16x16x32_bf16 v[70:73], v[174:177], v[236:239], v[70:73]
	v_mfma_f32_16x16x32_bf16 v[66:69], v[182:185], v[236:239], v[66:69]
	s_setprio 0
	s_barrier
	s_add_i32 s34, s56, s27
	v_lshl_add_u64 v[224:225], v[224:225], 0, s[96:97]
	s_mov_b32 m0, s34
	ds_read_b128 v[186:189], v157 offset:49152
	ds_read_b128 v[190:193], v157 offset:50176
	ds_read_b128 v[194:197], v157 offset:51200
	ds_read_b128 v[198:201], v157 offset:52224
	ds_read_b128 v[202:205], v157 offset:53248
	ds_read_b128 v[206:209], v157 offset:54272
	ds_read_b128 v[220:223], v157 offset:55296
	ds_read_b128 v[236:239], v157 offset:56320
	global_load_lds_dwordx4 v[224:225], off
	s_add_i32 m0, s34, 0x2000
	s_add_u32 s30, s30, 0x40080
	v_lshl_add_u64 v[224:225], v[230:231], 0, s[96:97]
	s_addc_u32 s31, s31, 0
	s_add_i32 s34, s57, s27
	global_load_lds_dwordx4 v[224:225], off
	v_lshl_add_u64 v[224:225], s[30:31], 0, v[132:133]
	s_mov_b32 m0, s34
	s_nop 0
	global_load_lds_dwordx4 v[224:225], off
	v_lshl_add_u64 v[224:225], s[30:31], 0, v[136:137]
	s_add_i32 m0, s34, 0x2000
	s_nop 0
	global_load_lds_dwordx4 v[224:225], off
	v_lshl_add_u64 v[224:225], v[240:241], 0, s[96:97]
	s_mov_b32 m0, s47
	s_nop 0
	global_load_lds_dwordx4 v[224:225], off
	v_lshl_add_u64 v[224:225], v[242:243], 0, s[96:97]
	s_mov_b32 m0, s48
	s_nop 0
	global_load_lds_dwordx4 v[224:225], off
	s_waitcnt vmcnt(8)
	s_waitcnt lgkmcnt(0)
	s_barrier
	s_setprio 1
	s_waitcnt lgkmcnt(0)
	v_mfma_f32_16x16x32_bf16 v[62:65], v[142:145], v[186:189], v[62:65]
	v_mfma_f32_16x16x32_bf16 v[58:61], v[162:165], v[186:189], v[58:61]
	v_mfma_f32_16x16x32_bf16 v[46:49], v[142:145], v[194:197], v[46:49]
	v_mfma_f32_16x16x32_bf16 v[42:45], v[162:165], v[194:197], v[42:45]
	v_mfma_f32_16x16x32_bf16 v[30:33], v[142:145], v[202:205], v[30:33]
	v_mfma_f32_16x16x32_bf16 v[26:29], v[162:165], v[202:205], v[26:29]
	v_mfma_f32_16x16x32_bf16 v[14:17], v[142:145], v[220:223], v[14:17]
	v_mfma_f32_16x16x32_bf16 v[10:13], v[162:165], v[220:223], v[10:13]
	v_mfma_f32_16x16x32_bf16 v[62:65], v[158:161], v[190:193], v[62:65]
	v_mfma_f32_16x16x32_bf16 v[58:61], v[166:169], v[190:193], v[58:61]
	v_mfma_f32_16x16x32_bf16 v[46:49], v[158:161], v[198:201], v[46:49]
	v_mfma_f32_16x16x32_bf16 v[42:45], v[166:169], v[198:201], v[42:45]
	v_mfma_f32_16x16x32_bf16 v[30:33], v[158:161], v[206:209], v[30:33]
	v_mfma_f32_16x16x32_bf16 v[26:29], v[166:169], v[206:209], v[26:29]
	v_mfma_f32_16x16x32_bf16 v[14:17], v[158:161], v[236:239], v[14:17]
	v_mfma_f32_16x16x32_bf16 v[10:13], v[166:169], v[236:239], v[10:13]
	s_setprio 0
	s_setprio 1
	v_mfma_f32_16x16x32_bf16 v[54:57], v[170:173], v[186:189], v[54:57]
	v_mfma_f32_16x16x32_bf16 v[50:53], v[178:181], v[186:189], v[50:53]
	v_mfma_f32_16x16x32_bf16 v[38:41], v[170:173], v[194:197], v[38:41]
	v_mfma_f32_16x16x32_bf16 v[34:37], v[178:181], v[194:197], v[34:37]
	v_mfma_f32_16x16x32_bf16 v[22:25], v[170:173], v[202:205], v[22:25]
	v_mfma_f32_16x16x32_bf16 v[18:21], v[178:181], v[202:205], v[18:21]
	v_mfma_f32_16x16x32_bf16 v[6:9], v[170:173], v[220:223], v[6:9]
	v_mfma_f32_16x16x32_bf16 v[2:5], v[178:181], v[220:223], v[2:5]
	v_mfma_f32_16x16x32_bf16 v[54:57], v[174:177], v[190:193], v[54:57]
	v_mfma_f32_16x16x32_bf16 v[50:53], v[182:185], v[190:193], v[50:53]
	v_mfma_f32_16x16x32_bf16 v[38:41], v[174:177], v[198:201], v[38:41]
	v_mfma_f32_16x16x32_bf16 v[34:37], v[182:185], v[198:201], v[34:37]
	v_mfma_f32_16x16x32_bf16 v[22:25], v[174:177], v[206:209], v[22:25]
	v_mfma_f32_16x16x32_bf16 v[18:21], v[182:185], v[206:209], v[18:21]
	v_mfma_f32_16x16x32_bf16 v[6:9], v[174:177], v[236:239], v[6:9]
	v_mfma_f32_16x16x32_bf16 v[2:5], v[182:185], v[236:239], v[2:5]
	s_setprio 0
	s_barrier
	s_add_i32 s55, s55, 2
	s_add_u32 s38, s38, 0x100
	s_addc_u32 s39, s39, 0
	s_add_u32 s28, s28, 0x100
	s_addc_u32 s29, s29, 0
	s_cmp_gt_u32 s55, 13
	s_cbranch_scc0 .LBB0_288
	s_and_b64 vcc, exec, s[12:13]
	s_cbranch_vccz .LBB0_291
	s_barrier

.LBB0_362:
	s_ashr_i32 s23, s22, 31
	s_lshl_b64 s[24:25], s[22:23], 19
	s_add_u32 s24, s80, s24
	s_addc_u32 s25, s81, s25
	s_and_b64 s[26:27], s[6:7], exec
	s_cselect_b32 s23, s25, s35
	s_cselect_b32 s39, s24, s34
	s_ashr_i32 s21, s20, 31
	s_lshl_b64 s[26:27], s[20:21], 19
	s_add_u32 s26, s45, s26
	s_addc_u32 s27, s46, s27
	s_and_b64 s[36:37], s[6:7], exec
	s_cselect_b32 s21, s27, s31
	s_cselect_b32 s40, s26, s30
	s_add_u32 s41, s30, 0x100
	s_addc_u32 s43, s31, 0
	s_add_u32 s30, s34, 0x40080
	s_addc_u32 s31, s35, 0
	s_mov_b32 s56, -2
.LBB0_363:
	s_add_u32 s34, s30, 0xfffc0080
	s_addc_u32 s35, s31, -1
	s_add_i32 s57, 0, 0x10000
	s_cmp_eq_u32 s56, 12
	s_cselect_b32 s37, s23, s35
	s_cselect_b32 s36, s39, s34
	v_add_u32_e32 v146, s57, v155
	s_cselect_b32 s35, s21, s43
	s_cselect_b32 s34, s40, s41
	s_add_i32 s60, 0, 0x14000
	ds_read_b128 v[142:145], v146
	ds_read_b128 v[168:171], v146 offset:1024
	ds_read_b128 v[172:175], v146 offset:2048
	ds_read_b128 v[176:179], v146 offset:3072
	v_add_u32_e32 v146, s60, v155
	ds_read_b128 v[180:183], v146
	ds_read_b128 v[184:187], v146 offset:1024
	ds_read_b128 v[188:191], v146 offset:2048
	ds_read_b128 v[192:195], v146 offset:3072
	v_lshl_add_u64 v[146:147], s[30:31], 0, v[140:141]
	s_add_i32 m0, s48, 0xc000
	ds_read_b128 v[196:199], v157
	ds_read_b128 v[200:203], v157 offset:1024
	ds_read_b128 v[204:207], v157 offset:2048
	ds_read_b128 v[220:223], v157 offset:3072
	ds_read_b128 v[236:239], v157 offset:4096
	ds_read_b128 v[240:243], v157 offset:5120
	ds_read_b128 v[244:247], v157 offset:6144
	ds_read_b128 v[248:251], v157 offset:7168
	global_load_lds_dwordx4 v[146:147], off
	v_lshl_add_u64 v[146:147], s[30:31], 0, v[138:139]
	s_add_i32 m0, s48, 0xe000
	s_nop 0
	global_load_lds_dwordx4 v[146:147], off
	s_cmp_lg_u32 s56, -2
	s_cbranch_scc1 .Lzf0_0
	v_mov_b32_e32 v66, 0
	v_mov_b32_e32 v67, 0
	v_mov_b32_e32 v68, 0
	v_mov_b32_e32 v69, 0
	v_mov_b32_e32 v70, 0
	v_mov_b32_e32 v71, 0
	v_mov_b32_e32 v72, 0
	v_mov_b32_e32 v73, 0
	v_mov_b32_e32 v74, 0
	v_mov_b32_e32 v75, 0
	v_mov_b32_e32 v76, 0
	v_mov_b32_e32 v77, 0
	v_mov_b32_e32 v78, 0
	v_mov_b32_e32 v79, 0
	v_mov_b32_e32 v80, 0
	v_mov_b32_e32 v81, 0
	v_mov_b32_e32 v82, 0
	v_mov_b32_e32 v83, 0
	v_mov_b32_e32 v84, 0
	v_mov_b32_e32 v85, 0
	v_mov_b32_e32 v86, 0
	v_mov_b32_e32 v87, 0
	v_mov_b32_e32 v88, 0
	v_mov_b32_e32 v89, 0
	v_mov_b32_e32 v90, 0
	v_mov_b32_e32 v91, 0
	v_mov_b32_e32 v92, 0
	v_mov_b32_e32 v93, 0
	v_mov_b32_e32 v94, 0
	v_mov_b32_e32 v95, 0
	v_mov_b32_e32 v96, 0
	v_mov_b32_e32 v97, 0
	v_mov_b32_e32 v98, 0
	v_mov_b32_e32 v99, 0
	v_mov_b32_e32 v100, 0
	v_mov_b32_e32 v101, 0
	v_mov_b32_e32 v102, 0
	v_mov_b32_e32 v103, 0
	v_mov_b32_e32 v104, 0
	v_mov_b32_e32 v105, 0
	v_mov_b32_e32 v106, 0
	v_mov_b32_e32 v107, 0
	v_mov_b32_e32 v108, 0
	v_mov_b32_e32 v109, 0
	v_mov_b32_e32 v110, 0
	v_mov_b32_e32 v111, 0
	v_mov_b32_e32 v112, 0
	v_mov_b32_e32 v113, 0
	v_mov_b32_e32 v114, 0
	v_mov_b32_e32 v115, 0
	v_mov_b32_e32 v116, 0
	v_mov_b32_e32 v117, 0
	v_mov_b32_e32 v118, 0
	v_mov_b32_e32 v119, 0
	v_mov_b32_e32 v120, 0
	v_mov_b32_e32 v121, 0
	v_mov_b32_e32 v122, 0
	v_mov_b32_e32 v123, 0
	v_mov_b32_e32 v124, 0
	v_mov_b32_e32 v125, 0
	v_mov_b32_e32 v126, 0
	v_mov_b32_e32 v127, 0
	v_mov_b32_e32 v128, 0
	v_mov_b32_e32 v129, 0
.Lzf0_0:
	s_waitcnt vmcnt(8)
	s_waitcnt lgkmcnt(0)
	s_barrier
	s_setprio 1
	s_waitcnt lgkmcnt(0)
	v_mfma_f32_16x16x32_bf16 v[126:129], v[142:145], v[196:199], v[126:129]
	v_mfma_f32_16x16x32_bf16 v[118:121], v[172:175], v[196:199], v[118:121]
	v_mfma_f32_16x16x32_bf16 v[110:113], v[142:145], v[204:207], v[110:113]
	v_mfma_f32_16x16x32_bf16 v[102:105], v[172:175], v[204:207], v[102:105]
	v_mfma_f32_16x16x32_bf16 v[94:97], v[142:145], v[236:239], v[94:97]
	v_mfma_f32_16x16x32_bf16 v[86:89], v[172:175], v[236:239], v[86:89]
	v_mfma_f32_16x16x32_bf16 v[78:81], v[142:145], v[244:247], v[78:81]
	v_mfma_f32_16x16x32_bf16 v[70:73], v[172:175], v[244:247], v[70:73]
	v_mfma_f32_16x16x32_bf16 v[126:129], v[168:171], v[200:203], v[126:129]
	v_mfma_f32_16x16x32_bf16 v[118:121], v[176:179], v[200:203], v[118:121]
	v_mfma_f32_16x16x32_bf16 v[110:113], v[168:171], v[220:223], v[110:113]
	v_mfma_f32_16x16x32_bf16 v[102:105], v[176:179], v[220:223], v[102:105]
	v_mfma_f32_16x16x32_bf16 v[94:97], v[168:171], v[240:243], v[94:97]
	v_mfma_f32_16x16x32_bf16 v[86:89], v[176:179], v[240:243], v[86:89]
	v_mfma_f32_16x16x32_bf16 v[78:81], v[168:171], v[248:251], v[78:81]
	v_mfma_f32_16x16x32_bf16 v[70:73], v[176:179], v[248:251], v[70:73]
	s_setprio 0
	s_setprio 1
	v_mfma_f32_16x16x32_bf16 v[122:125], v[180:183], v[196:199], v[122:125]
	v_mfma_f32_16x16x32_bf16 v[114:117], v[188:191], v[196:199], v[114:117]
	v_mfma_f32_16x16x32_bf16 v[106:109], v[180:183], v[204:207], v[106:109]
	v_mfma_f32_16x16x32_bf16 v[98:101], v[188:191], v[204:207], v[98:101]
	v_mfma_f32_16x16x32_bf16 v[90:93], v[180:183], v[236:239], v[90:93]
	v_mfma_f32_16x16x32_bf16 v[82:85], v[188:191], v[236:239], v[82:85]
	v_mfma_f32_16x16x32_bf16 v[74:77], v[180:183], v[244:247], v[74:77]
	v_mfma_f32_16x16x32_bf16 v[66:69], v[188:191], v[244:247], v[66:69]
	v_mfma_f32_16x16x32_bf16 v[122:125], v[184:187], v[200:203], v[122:125]
	v_mfma_f32_16x16x32_bf16 v[114:117], v[192:195], v[200:203], v[114:117]
	v_mfma_f32_16x16x32_bf16 v[106:109], v[184:187], v[220:223], v[106:109]
	v_mfma_f32_16x16x32_bf16 v[98:101], v[192:195], v[220:223], v[98:101]
	v_mfma_f32_16x16x32_bf16 v[90:93], v[184:187], v[240:243], v[90:93]
	v_mfma_f32_16x16x32_bf16 v[82:85], v[192:195], v[240:243], v[82:85]
	v_mfma_f32_16x16x32_bf16 v[74:77], v[184:187], v[248:251], v[74:77]
	v_mfma_f32_16x16x32_bf16 v[66:69], v[192:195], v[248:251], v[66:69]
	s_setprio 0
	s_barrier
	s_add_i32 s57, s57, s44
	v_lshl_add_u64 v[146:147], s[34:35], 0, v[134:135]
	s_mov_b32 m0, s57
	ds_read_b128 v[196:199], v157 offset:16384
	ds_read_b128 v[200:203], v157 offset:17408
	ds_read_b128 v[204:207], v157 offset:18432
	ds_read_b128 v[220:223], v157 offset:19456
	ds_read_b128 v[236:239], v157 offset:20480
	ds_read_b128 v[240:243], v157 offset:21504
	ds_read_b128 v[244:247], v157 offset:22528
	ds_read_b128 v[248:251], v157 offset:23552
	global_load_lds_dwordx4 v[146:147], off
	s_add_i32 m0, s57, 0x2000
	s_add_u32 s58, s34, 0x40000
	v_lshl_add_u64 v[208:209], s[34:35], 0, v[130:131]
	s_addc_u32 s59, s35, 0
	s_add_i32 s57, s60, s44
	global_load_lds_dwordx4 v[208:209], off
	v_lshl_add_u64 v[224:225], s[58:59], 0, v[134:135]
	s_mov_b32 m0, s57
	v_lshl_add_u64 v[230:231], s[36:37], 0, v[132:133]
	global_load_lds_dwordx4 v[224:225], off
	v_lshl_add_u64 v[224:225], s[58:59], 0, v[130:131]
	s_add_i32 m0, s57, 0x2000
	s_nop 0
	global_load_lds_dwordx4 v[224:225], off
	v_lshl_add_u64 v[224:225], s[36:37], 0, v[136:137]
	s_mov_b32 m0, s48
	s_nop 0
	global_load_lds_dwordx4 v[224:225], off
	s_mov_b32 m0, s49
	s_nop 0
	global_load_lds_dwordx4 v[230:231], off
	s_cmp_lg_u32 s56, -2
	s_cbranch_scc1 .Lzf0_1
	v_mov_b32_e32 v2, 0
	v_mov_b32_e32 v3, 0
	v_mov_b32_e32 v4, 0
	v_mov_b32_e32 v5, 0
	v_mov_b32_e32 v6, 0
	v_mov_b32_e32 v7, 0
	v_mov_b32_e32 v8, 0
	v_mov_b32_e32 v9, 0
	v_mov_b32_e32 v10, 0
	v_mov_b32_e32 v11, 0
	v_mov_b32_e32 v12, 0
	v_mov_b32_e32 v13, 0
	v_mov_b32_e32 v14, 0
	v_mov_b32_e32 v15, 0
	v_mov_b32_e32 v16, 0
	v_mov_b32_e32 v17, 0
	v_mov_b32_e32 v18, 0
	v_mov_b32_e32 v19, 0
	v_mov_b32_e32 v20, 0
	v_mov_b32_e32 v21, 0
	v_mov_b32_e32 v22, 0
	v_mov_b32_e32 v23, 0
	v_mov_b32_e32 v24, 0
	v_mov_b32_e32 v25, 0
	v_mov_b32_e32 v26, 0
	v_mov_b32_e32 v27, 0
	v_mov_b32_e32 v28, 0
	v_mov_b32_e32 v29, 0
	v_mov_b32_e32 v30, 0
	v_mov_b32_e32 v31, 0
	v_mov_b32_e32 v32, 0
	v_mov_b32_e32 v33, 0
	v_mov_b32_e32 v34, 0
	v_mov_b32_e32 v35, 0
	v_mov_b32_e32 v36, 0
	v_mov_b32_e32 v37, 0
	v_mov_b32_e32 v38, 0
	v_mov_b32_e32 v39, 0
	v_mov_b32_e32 v40, 0
	v_mov_b32_e32 v41, 0
	v_mov_b32_e32 v42, 0
	v_mov_b32_e32 v43, 0
	v_mov_b32_e32 v44, 0
	v_mov_b32_e32 v45, 0
	v_mov_b32_e32 v46, 0
	v_mov_b32_e32 v47, 0
	v_mov_b32_e32 v48, 0
	v_mov_b32_e32 v49, 0
	v_mov_b32_e32 v50, 0
	v_mov_b32_e32 v51, 0
	v_mov_b32_e32 v52, 0
	v_mov_b32_e32 v53, 0
	v_mov_b32_e32 v54, 0
	v_mov_b32_e32 v55, 0
	v_mov_b32_e32 v56, 0
	v_mov_b32_e32 v57, 0
	v_mov_b32_e32 v58, 0
	v_mov_b32_e32 v59, 0
	v_mov_b32_e32 v60, 0
	v_mov_b32_e32 v61, 0
	v_mov_b32_e32 v62, 0
	v_mov_b32_e32 v63, 0
	v_mov_b32_e32 v64, 0
	v_mov_b32_e32 v65, 0
.Lzf0_1:
	s_waitcnt vmcnt(8)
	s_waitcnt lgkmcnt(0)
	s_barrier
	s_setprio 1
	s_waitcnt lgkmcnt(0)
	v_mfma_f32_16x16x32_bf16 v[62:65], v[142:145], v[196:199], v[62:65]
	v_mfma_f32_16x16x32_bf16 v[54:57], v[172:175], v[196:199], v[54:57]
	v_mfma_f32_16x16x32_bf16 v[46:49], v[142:145], v[204:207], v[46:49]
	v_mfma_f32_16x16x32_bf16 v[38:41], v[172:175], v[204:207], v[38:41]
	v_mfma_f32_16x16x32_bf16 v[30:33], v[142:145], v[236:239], v[30:33]
	v_mfma_f32_16x16x32_bf16 v[22:25], v[172:175], v[236:239], v[22:25]
	v_mfma_f32_16x16x32_bf16 v[14:17], v[142:145], v[244:247], v[14:17]
	v_mfma_f32_16x16x32_bf16 v[6:9], v[172:175], v[244:247], v[6:9]
	v_mfma_f32_16x16x32_bf16 v[62:65], v[168:171], v[200:203], v[62:65]
	v_mfma_f32_16x16x32_bf16 v[54:57], v[176:179], v[200:203], v[54:57]
	v_mfma_f32_16x16x32_bf16 v[46:49], v[168:171], v[220:223], v[46:49]
	v_mfma_f32_16x16x32_bf16 v[38:41], v[176:179], v[220:223], v[38:41]
	v_mfma_f32_16x16x32_bf16 v[30:33], v[168:171], v[240:243], v[30:33]
	v_mfma_f32_16x16x32_bf16 v[22:25], v[176:179], v[240:243], v[22:25]
	v_mfma_f32_16x16x32_bf16 v[14:17], v[168:171], v[248:251], v[14:17]
	v_mfma_f32_16x16x32_bf16 v[6:9], v[176:179], v[248:251], v[6:9]
	s_setprio 0
	s_setprio 1
	v_mfma_f32_16x16x32_bf16 v[58:61], v[180:183], v[196:199], v[58:61]
	v_mfma_f32_16x16x32_bf16 v[50:53], v[188:191], v[196:199], v[50:53]
	v_mfma_f32_16x16x32_bf16 v[42:45], v[180:183], v[204:207], v[42:45]
	v_mfma_f32_16x16x32_bf16 v[34:37], v[188:191], v[204:207], v[34:37]
	v_mfma_f32_16x16x32_bf16 v[26:29], v[180:183], v[236:239], v[26:29]
	v_mfma_f32_16x16x32_bf16 v[18:21], v[188:191], v[236:239], v[18:21]
	v_mfma_f32_16x16x32_bf16 v[10:13], v[180:183], v[244:247], v[10:13]
	v_mfma_f32_16x16x32_bf16 v[2:5], v[188:191], v[244:247], v[2:5]
	v_mfma_f32_16x16x32_bf16 v[58:61], v[184:187], v[200:203], v[58:61]
	v_mfma_f32_16x16x32_bf16 v[50:53], v[192:195], v[200:203], v[50:53]
	v_mfma_f32_16x16x32_bf16 v[42:45], v[184:187], v[220:223], v[42:45]
	v_mfma_f32_16x16x32_bf16 v[34:37], v[192:195], v[220:223], v[34:37]
	v_mfma_f32_16x16x32_bf16 v[26:29], v[184:187], v[240:243], v[26:29]
	v_mfma_f32_16x16x32_bf16 v[18:21], v[192:195], v[240:243], v[18:21]
	v_mfma_f32_16x16x32_bf16 v[10:13], v[184:187], v[248:251], v[10:13]
	v_mfma_f32_16x16x32_bf16 v[2:5], v[192:195], v[248:251], v[2:5]
	s_setprio 0
	s_barrier
	s_add_i32 s57, 0, 0x18000
	v_add_u32_e32 v164, s57, v155
	s_add_i32 s58, 0, 0x1c000
	ds_read_b128 v[142:145], v164
	ds_read_b128 v[168:171], v164 offset:1024
	ds_read_b128 v[172:175], v164 offset:2048
	ds_read_b128 v[176:179], v164 offset:3072
	v_add_u32_e32 v164, s58, v155
	ds_read_b128 v[180:183], v164
	ds_read_b128 v[184:187], v164 offset:1024
	ds_read_b128 v[188:191], v164 offset:2048
	ds_read_b128 v[192:195], v164 offset:3072
	s_add_u32 s36, s36, 0x40000
	s_addc_u32 s37, s37, 0
	s_mov_b32 m0, s50
	v_lshl_add_u64 v[252:253], s[36:37], 0, v[136:137]
	ds_read_b128 v[196:199], v157 offset:32768
	ds_read_b128 v[200:203], v157 offset:33792
	ds_read_b128 v[204:207], v157 offset:34816
	ds_read_b128 v[220:223], v157 offset:35840
	ds_read_b128 v[236:239], v157 offset:36864
	ds_read_b128 v[240:243], v157 offset:37888
	ds_read_b128 v[244:247], v157 offset:38912
	ds_read_b128 v[248:251], v157 offset:39936
	global_load_lds_dwordx4 v[252:253], off
	v_lshl_add_u64 v[252:253], s[36:37], 0, v[132:133]
	s_mov_b32 m0, s51
	s_nop 0
	global_load_lds_dwordx4 v[252:253], off
	s_waitcnt vmcnt(8)
	s_waitcnt lgkmcnt(0)
	s_barrier
	s_setprio 1
	s_waitcnt lgkmcnt(0)
	v_mfma_f32_16x16x32_bf16 v[126:129], v[142:145], v[196:199], v[126:129]
	v_mfma_f32_16x16x32_bf16 v[118:121], v[172:175], v[196:199], v[118:121]
	v_mfma_f32_16x16x32_bf16 v[110:113], v[142:145], v[204:207], v[110:113]
	v_mfma_f32_16x16x32_bf16 v[102:105], v[172:175], v[204:207], v[102:105]
	v_mfma_f32_16x16x32_bf16 v[94:97], v[142:145], v[236:239], v[94:97]
	v_mfma_f32_16x16x32_bf16 v[86:89], v[172:175], v[236:239], v[86:89]
	v_mfma_f32_16x16x32_bf16 v[78:81], v[142:145], v[244:247], v[78:81]
	v_mfma_f32_16x16x32_bf16 v[70:73], v[172:175], v[244:247], v[70:73]
	v_mfma_f32_16x16x32_bf16 v[126:129], v[168:171], v[200:203], v[126:129]
	v_mfma_f32_16x16x32_bf16 v[118:121], v[176:179], v[200:203], v[118:121]
	v_mfma_f32_16x16x32_bf16 v[110:113], v[168:171], v[220:223], v[110:113]
	v_mfma_f32_16x16x32_bf16 v[102:105], v[176:179], v[220:223], v[102:105]
	v_mfma_f32_16x16x32_bf16 v[94:97], v[168:171], v[240:243], v[94:97]
	v_mfma_f32_16x16x32_bf16 v[86:89], v[176:179], v[240:243], v[86:89]
	v_mfma_f32_16x16x32_bf16 v[78:81], v[168:171], v[248:251], v[78:81]
	v_mfma_f32_16x16x32_bf16 v[70:73], v[176:179], v[248:251], v[70:73]
	s_setprio 0
	s_setprio 1
	v_mfma_f32_16x16x32_bf16 v[122:125], v[180:183], v[196:199], v[122:125]
	v_mfma_f32_16x16x32_bf16 v[114:117], v[188:191], v[196:199], v[114:117]
	v_mfma_f32_16x16x32_bf16 v[106:109], v[180:183], v[204:207], v[106:109]
	v_mfma_f32_16x16x32_bf16 v[98:101], v[188:191], v[204:207], v[98:101]
	v_mfma_f32_16x16x32_bf16 v[90:93], v[180:183], v[236:239], v[90:93]
	v_mfma_f32_16x16x32_bf16 v[82:85], v[188:191], v[236:239], v[82:85]
	v_mfma_f32_16x16x32_bf16 v[74:77], v[180:183], v[244:247], v[74:77]
	v_mfma_f32_16x16x32_bf16 v[66:69], v[188:191], v[244:247], v[66:69]
	v_mfma_f32_16x16x32_bf16 v[122:125], v[184:187], v[200:203], v[122:125]
	v_mfma_f32_16x16x32_bf16 v[114:117], v[192:195], v[200:203], v[114:117]
	v_mfma_f32_16x16x32_bf16 v[106:109], v[184:187], v[220:223], v[106:109]
	v_mfma_f32_16x16x32_bf16 v[98:101], v[192:195], v[220:223], v[98:101]
	v_mfma_f32_16x16x32_bf16 v[90:93], v[184:187], v[240:243], v[90:93]
	v_mfma_f32_16x16x32_bf16 v[82:85], v[192:195], v[240:243], v[82:85]
	v_mfma_f32_16x16x32_bf16 v[74:77], v[184:187], v[248:251], v[74:77]
	v_mfma_f32_16x16x32_bf16 v[66:69], v[192:195], v[248:251], v[66:69]
	s_setprio 0
	s_barrier
	s_add_i32 s36, s57, s44
	v_lshl_add_u64 v[146:147], v[146:147], 0, s[96:97]
	s_mov_b32 m0, s36
	ds_read_b128 v[196:199], v157 offset:49152
	ds_read_b128 v[200:203], v157 offset:50176
	ds_read_b128 v[204:207], v157 offset:51200
	ds_read_b128 v[220:223], v157 offset:52224
	ds_read_b128 v[236:239], v157 offset:53248
	ds_read_b128 v[240:243], v157 offset:54272
	ds_read_b128 v[244:247], v157 offset:55296
	ds_read_b128 v[248:251], v157 offset:56320
	global_load_lds_dwordx4 v[146:147], off
	s_add_i32 m0, s36, 0x2000
	s_add_u32 s34, s34, 0x40080
	v_lshl_add_u64 v[146:147], v[208:209], 0, s[96:97]
	s_addc_u32 s35, s35, 0
	s_add_i32 s36, s58, s44
	global_load_lds_dwordx4 v[146:147], off
	v_lshl_add_u64 v[146:147], s[34:35], 0, v[134:135]
	s_mov_b32 m0, s36
	s_nop 0
	global_load_lds_dwordx4 v[146:147], off
	v_lshl_add_u64 v[146:147], s[34:35], 0, v[130:131]
	s_add_i32 m0, s36, 0x2000
	s_nop 0
	global_load_lds_dwordx4 v[146:147], off
	v_lshl_add_u64 v[146:147], v[224:225], 0, s[96:97]
	s_mov_b32 m0, s52
	s_nop 0
	global_load_lds_dwordx4 v[146:147], off
	v_lshl_add_u64 v[146:147], v[230:231], 0, s[96:97]
	s_mov_b32 m0, s53
	s_nop 0
	global_load_lds_dwordx4 v[146:147], off
	s_waitcnt vmcnt(8)
	s_waitcnt lgkmcnt(0)
	s_barrier
	s_setprio 1
	s_waitcnt lgkmcnt(0)
	v_mfma_f32_16x16x32_bf16 v[62:65], v[142:145], v[196:199], v[62:65]
	v_mfma_f32_16x16x32_bf16 v[54:57], v[172:175], v[196:199], v[54:57]
	v_mfma_f32_16x16x32_bf16 v[46:49], v[142:145], v[204:207], v[46:49]
	v_mfma_f32_16x16x32_bf16 v[38:41], v[172:175], v[204:207], v[38:41]
	v_mfma_f32_16x16x32_bf16 v[30:33], v[142:145], v[236:239], v[30:33]
	v_mfma_f32_16x16x32_bf16 v[22:25], v[172:175], v[236:239], v[22:25]
	v_mfma_f32_16x16x32_bf16 v[14:17], v[142:145], v[244:247], v[14:17]
	v_mfma_f32_16x16x32_bf16 v[6:9], v[172:175], v[244:247], v[6:9]
	v_mfma_f32_16x16x32_bf16 v[62:65], v[168:171], v[200:203], v[62:65]
	v_mfma_f32_16x16x32_bf16 v[54:57], v[176:179], v[200:203], v[54:57]
	v_mfma_f32_16x16x32_bf16 v[46:49], v[168:171], v[220:223], v[46:49]
	v_mfma_f32_16x16x32_bf16 v[38:41], v[176:179], v[220:223], v[38:41]
	v_mfma_f32_16x16x32_bf16 v[30:33], v[168:171], v[240:243], v[30:33]
	v_mfma_f32_16x16x32_bf16 v[22:25], v[176:179], v[240:243], v[22:25]
	v_mfma_f32_16x16x32_bf16 v[14:17], v[168:171], v[248:251], v[14:17]
	v_mfma_f32_16x16x32_bf16 v[6:9], v[176:179], v[248:251], v[6:9]
	s_setprio 0
	s_setprio 1
	v_mfma_f32_16x16x32_bf16 v[58:61], v[180:183], v[196:199], v[58:61]
	v_mfma_f32_16x16x32_bf16 v[50:53], v[188:191], v[196:199], v[50:53]
	v_mfma_f32_16x16x32_bf16 v[42:45], v[180:183], v[204:207], v[42:45]
	v_mfma_f32_16x16x32_bf16 v[34:37], v[188:191], v[204:207], v[34:37]
	v_mfma_f32_16x16x32_bf16 v[26:29], v[180:183], v[236:239], v[26:29]
	v_mfma_f32_16x16x32_bf16 v[18:21], v[188:191], v[236:239], v[18:21]
	v_mfma_f32_16x16x32_bf16 v[10:13], v[180:183], v[244:247], v[10:13]
	v_mfma_f32_16x16x32_bf16 v[2:5], v[188:191], v[244:247], v[2:5]
	v_mfma_f32_16x16x32_bf16 v[58:61], v[184:187], v[200:203], v[58:61]
	v_mfma_f32_16x16x32_bf16 v[50:53], v[192:195], v[200:203], v[50:53]
	v_mfma_f32_16x16x32_bf16 v[42:45], v[184:187], v[220:223], v[42:45]
	v_mfma_f32_16x16x32_bf16 v[34:37], v[192:195], v[220:223], v[34:37]
	v_mfma_f32_16x16x32_bf16 v[26:29], v[184:187], v[240:243], v[26:29]
	v_mfma_f32_16x16x32_bf16 v[18:21], v[192:195], v[240:243], v[18:21]
	v_mfma_f32_16x16x32_bf16 v[10:13], v[184:187], v[248:251], v[10:13]
	v_mfma_f32_16x16x32_bf16 v[2:5], v[192:195], v[248:251], v[2:5]
	s_setprio 0
	s_barrier
	s_add_i32 s56, s56, 2
	s_add_u32 s41, s41, 0x100
	s_addc_u32 s43, s43, 0
	s_add_u32 s30, s30, 0x100
	s_addc_u32 s31, s31, 0
	s_cmp_gt_u32 s56, 13
	s_cbranch_scc0 .LBB0_363
	s_and_b64 vcc, exec, s[16:17]
	s_cbranch_vccz .LBB0_366
	s_barrier

.LBB0_639:
	s_ashr_i32 s13, s12, 31
	s_lshl_b64 s[14:15], s[12:13], 19
	s_add_u32 s14, s80, s14
	s_addc_u32 s15, s81, s15
	s_and_b64 s[16:17], s[4:5], exec
	s_cselect_b32 s13, s15, s23
	s_cselect_b32 s19, s14, s22
	s_ashr_i32 s11, s10, 31
	s_lshl_b64 s[16:17], s[10:11], 19
	s_add_u32 s16, s26, s16
	s_addc_u32 s17, s27, s17
	s_and_b64 s[24:25], s[4:5], exec
	s_cselect_b32 s11, s17, s21
	s_cselect_b32 s41, s16, s20
	s_add_u32 s43, s20, 0x100
	s_addc_u32 s44, s21, 0
	s_add_u32 s20, s22, 0x40080
	s_addc_u32 s21, s23, 0
	s_mov_b32 s45, -2
.LBB0_640:
	s_add_u32 s22, s20, 0xfffc0080
	s_addc_u32 s23, s21, -1
	s_add_i32 s46, 0, 0x10000
	s_cmp_eq_u32 s45, 12
	s_cselect_b32 s25, s13, s23
	s_cselect_b32 s24, s19, s22
	v_add_u32_e32 v150, s46, v159
	s_cselect_b32 s23, s11, s44
	s_cselect_b32 s22, s41, s43
	s_add_i32 s48, 0, 0x14000
	ds_read_b128 v[164:167], v150
	ds_read_b128 v[168:171], v150 offset:1024
	ds_read_b128 v[172:175], v150 offset:2048
	ds_read_b128 v[176:179], v150 offset:3072
	v_add_u32_e32 v150, s48, v159
	ds_read_b128 v[180:183], v150
	ds_read_b128 v[184:187], v150 offset:1024
	ds_read_b128 v[188:191], v150 offset:2048
	ds_read_b128 v[192:195], v150 offset:3072
	v_lshl_add_u64 v[150:151], s[20:21], 0, v[140:141]
	s_add_i32 m0, s30, 0xc000
	ds_read_b128 v[196:199], v162
	ds_read_b128 v[200:203], v162 offset:1024
	ds_read_b128 v[204:207], v162 offset:2048
	ds_read_b128 v[220:223], v162 offset:3072
	ds_read_b128 v[236:239], v162 offset:4096
	ds_read_b128 v[240:243], v162 offset:5120
	ds_read_b128 v[244:247], v162 offset:6144
	ds_read_b128 v[248:251], v162 offset:7168
	global_load_lds_dwordx4 v[150:151], off
	v_lshl_add_u64 v[150:151], s[20:21], 0, v[138:139]
	s_add_i32 m0, s30, 0xe000
	s_nop 0
	global_load_lds_dwordx4 v[150:151], off
	s_cmp_lg_u32 s45, -2
	s_cbranch_scc1 .Lzf2_0
	v_mov_b32_e32 v66, 0
	v_mov_b32_e32 v67, 0
	v_mov_b32_e32 v68, 0
	v_mov_b32_e32 v69, 0
	v_mov_b32_e32 v70, 0
	v_mov_b32_e32 v71, 0
	v_mov_b32_e32 v72, 0
	v_mov_b32_e32 v73, 0
	v_mov_b32_e32 v74, 0
	v_mov_b32_e32 v75, 0
	v_mov_b32_e32 v76, 0
	v_mov_b32_e32 v77, 0
	v_mov_b32_e32 v78, 0
	v_mov_b32_e32 v79, 0
	v_mov_b32_e32 v80, 0
	v_mov_b32_e32 v81, 0
	v_mov_b32_e32 v82, 0
	v_mov_b32_e32 v83, 0
	v_mov_b32_e32 v84, 0
	v_mov_b32_e32 v85, 0
	v_mov_b32_e32 v86, 0
	v_mov_b32_e32 v87, 0
	v_mov_b32_e32 v88, 0
	v_mov_b32_e32 v89, 0
	v_mov_b32_e32 v90, 0
	v_mov_b32_e32 v91, 0
	v_mov_b32_e32 v92, 0
	v_mov_b32_e32 v93, 0
	v_mov_b32_e32 v94, 0
	v_mov_b32_e32 v95, 0
	v_mov_b32_e32 v96, 0
	v_mov_b32_e32 v97, 0
	v_mov_b32_e32 v98, 0
	v_mov_b32_e32 v99, 0
	v_mov_b32_e32 v100, 0
	v_mov_b32_e32 v101, 0
	v_mov_b32_e32 v102, 0
	v_mov_b32_e32 v103, 0
	v_mov_b32_e32 v104, 0
	v_mov_b32_e32 v105, 0
	v_mov_b32_e32 v106, 0
	v_mov_b32_e32 v107, 0
	v_mov_b32_e32 v108, 0
	v_mov_b32_e32 v109, 0
	v_mov_b32_e32 v110, 0
	v_mov_b32_e32 v111, 0
	v_mov_b32_e32 v112, 0
	v_mov_b32_e32 v113, 0
	v_mov_b32_e32 v114, 0
	v_mov_b32_e32 v115, 0
	v_mov_b32_e32 v116, 0
	v_mov_b32_e32 v117, 0
	v_mov_b32_e32 v118, 0
	v_mov_b32_e32 v119, 0
	v_mov_b32_e32 v120, 0
	v_mov_b32_e32 v121, 0
	v_mov_b32_e32 v122, 0
	v_mov_b32_e32 v123, 0
	v_mov_b32_e32 v124, 0
	v_mov_b32_e32 v125, 0
	v_mov_b32_e32 v126, 0
	v_mov_b32_e32 v127, 0
	v_mov_b32_e32 v128, 0
	v_mov_b32_e32 v129, 0
.Lzf2_0:
	s_waitcnt vmcnt(8)
	s_waitcnt lgkmcnt(0)
	s_barrier
	s_setprio 1
	s_waitcnt lgkmcnt(0)
	v_mfma_f32_16x16x32_bf16 v[126:129], v[164:167], v[196:199], v[126:129]
	v_mfma_f32_16x16x32_bf16 v[122:125], v[172:175], v[196:199], v[122:125]
	v_mfma_f32_16x16x32_bf16 v[118:121], v[164:167], v[204:207], v[118:121]
	v_mfma_f32_16x16x32_bf16 v[114:117], v[172:175], v[204:207], v[114:117]
	v_mfma_f32_16x16x32_bf16 v[110:113], v[164:167], v[236:239], v[110:113]
	v_mfma_f32_16x16x32_bf16 v[106:109], v[172:175], v[236:239], v[106:109]
	v_mfma_f32_16x16x32_bf16 v[102:105], v[164:167], v[244:247], v[102:105]
	v_mfma_f32_16x16x32_bf16 v[98:101], v[172:175], v[244:247], v[98:101]
	v_mfma_f32_16x16x32_bf16 v[126:129], v[168:171], v[200:203], v[126:129]
	v_mfma_f32_16x16x32_bf16 v[122:125], v[176:179], v[200:203], v[122:125]
	v_mfma_f32_16x16x32_bf16 v[118:121], v[168:171], v[220:223], v[118:121]
	v_mfma_f32_16x16x32_bf16 v[114:117], v[176:179], v[220:223], v[114:117]
	v_mfma_f32_16x16x32_bf16 v[110:113], v[168:171], v[240:243], v[110:113]
	v_mfma_f32_16x16x32_bf16 v[106:109], v[176:179], v[240:243], v[106:109]
	v_mfma_f32_16x16x32_bf16 v[102:105], v[168:171], v[248:251], v[102:105]
	v_mfma_f32_16x16x32_bf16 v[98:101], v[176:179], v[248:251], v[98:101]
	s_setprio 0
	s_setprio 1
	v_mfma_f32_16x16x32_bf16 v[94:97], v[180:183], v[196:199], v[94:97]
	v_mfma_f32_16x16x32_bf16 v[90:93], v[188:191], v[196:199], v[90:93]
	v_mfma_f32_16x16x32_bf16 v[86:89], v[180:183], v[204:207], v[86:89]
	v_mfma_f32_16x16x32_bf16 v[82:85], v[188:191], v[204:207], v[82:85]
	v_mfma_f32_16x16x32_bf16 v[78:81], v[180:183], v[236:239], v[78:81]
	v_mfma_f32_16x16x32_bf16 v[74:77], v[188:191], v[236:239], v[74:77]
	v_mfma_f32_16x16x32_bf16 v[70:73], v[180:183], v[244:247], v[70:73]
	v_mfma_f32_16x16x32_bf16 v[66:69], v[188:191], v[244:247], v[66:69]
	v_mfma_f32_16x16x32_bf16 v[94:97], v[184:187], v[200:203], v[94:97]
	v_mfma_f32_16x16x32_bf16 v[90:93], v[192:195], v[200:203], v[90:93]
	v_mfma_f32_16x16x32_bf16 v[86:89], v[184:187], v[220:223], v[86:89]
	v_mfma_f32_16x16x32_bf16 v[82:85], v[192:195], v[220:223], v[82:85]
	v_mfma_f32_16x16x32_bf16 v[78:81], v[184:187], v[240:243], v[78:81]
	v_mfma_f32_16x16x32_bf16 v[74:77], v[192:195], v[240:243], v[74:77]
	v_mfma_f32_16x16x32_bf16 v[70:73], v[184:187], v[248:251], v[70:73]
	v_mfma_f32_16x16x32_bf16 v[66:69], v[192:195], v[248:251], v[66:69]
	s_setprio 0
	s_barrier
	s_add_i32 s46, s46, s28
	v_lshl_add_u64 v[150:151], s[22:23], 0, v[134:135]
	s_mov_b32 m0, s46
	ds_read_b128 v[196:199], v162 offset:16384
	ds_read_b128 v[200:203], v162 offset:17408
	ds_read_b128 v[204:207], v162 offset:18432
	ds_read_b128 v[220:223], v162 offset:19456
	ds_read_b128 v[236:239], v162 offset:20480
	ds_read_b128 v[240:243], v162 offset:21504
	ds_read_b128 v[244:247], v162 offset:22528
	ds_read_b128 v[248:251], v162 offset:23552
	global_load_lds_dwordx4 v[150:151], off
	s_add_i32 m0, s46, 0x2000
	s_add_u32 s46, s22, 0x40000
	v_lshl_add_u64 v[208:209], s[22:23], 0, v[130:131]
	s_addc_u32 s47, s23, 0
	s_add_i32 s48, s48, s28
	global_load_lds_dwordx4 v[208:209], off
	v_lshl_add_u64 v[224:225], s[46:47], 0, v[134:135]
	s_mov_b32 m0, s48
	v_lshl_add_u64 v[252:253], s[24:25], 0, v[132:133]
	global_load_lds_dwordx4 v[224:225], off
	v_lshl_add_u64 v[224:225], s[46:47], 0, v[130:131]
	s_add_i32 m0, s48, 0x2000
	s_nop 0
	global_load_lds_dwordx4 v[224:225], off
	v_lshl_add_u64 v[224:225], s[24:25], 0, v[136:137]
	s_mov_b32 m0, s30
	s_nop 0
	global_load_lds_dwordx4 v[224:225], off
	s_mov_b32 m0, s31
	s_nop 0
	global_load_lds_dwordx4 v[252:253], off
	s_cmp_lg_u32 s45, -2
	s_cbranch_scc1 .Lzf2_1
	v_mov_b32_e32 v2, 0
	v_mov_b32_e32 v3, 0
	v_mov_b32_e32 v4, 0
	v_mov_b32_e32 v5, 0
	v_mov_b32_e32 v6, 0
	v_mov_b32_e32 v7, 0
	v_mov_b32_e32 v8, 0
	v_mov_b32_e32 v9, 0
	v_mov_b32_e32 v10, 0
	v_mov_b32_e32 v11, 0
	v_mov_b32_e32 v12, 0
	v_mov_b32_e32 v13, 0
	v_mov_b32_e32 v14, 0
	v_mov_b32_e32 v15, 0
	v_mov_b32_e32 v16, 0
	v_mov_b32_e32 v17, 0
	v_mov_b32_e32 v18, 0
	v_mov_b32_e32 v19, 0
	v_mov_b32_e32 v20, 0
	v_mov_b32_e32 v21, 0
	v_mov_b32_e32 v22, 0
	v_mov_b32_e32 v23, 0
	v_mov_b32_e32 v24, 0
	v_mov_b32_e32 v25, 0
	v_mov_b32_e32 v26, 0
	v_mov_b32_e32 v27, 0
	v_mov_b32_e32 v28, 0
	v_mov_b32_e32 v29, 0
	v_mov_b32_e32 v30, 0
	v_mov_b32_e32 v31, 0
	v_mov_b32_e32 v32, 0
	v_mov_b32_e32 v33, 0
	v_mov_b32_e32 v34, 0
	v_mov_b32_e32 v35, 0
	v_mov_b32_e32 v36, 0
	v_mov_b32_e32 v37, 0
	v_mov_b32_e32 v38, 0
	v_mov_b32_e32 v39, 0
	v_mov_b32_e32 v40, 0
	v_mov_b32_e32 v41, 0
	v_mov_b32_e32 v42, 0
	v_mov_b32_e32 v43, 0
	v_mov_b32_e32 v44, 0
	v_mov_b32_e32 v45, 0
	v_mov_b32_e32 v46, 0
	v_mov_b32_e32 v47, 0
	v_mov_b32_e32 v48, 0
	v_mov_b32_e32 v49, 0
	v_mov_b32_e32 v50, 0
	v_mov_b32_e32 v51, 0
	v_mov_b32_e32 v52, 0
	v_mov_b32_e32 v53, 0
	v_mov_b32_e32 v54, 0
	v_mov_b32_e32 v55, 0
	v_mov_b32_e32 v56, 0
	v_mov_b32_e32 v57, 0
	v_mov_b32_e32 v58, 0
	v_mov_b32_e32 v59, 0
	v_mov_b32_e32 v60, 0
	v_mov_b32_e32 v61, 0
	v_mov_b32_e32 v62, 0
	v_mov_b32_e32 v63, 0
	v_mov_b32_e32 v64, 0
	v_mov_b32_e32 v65, 0
.Lzf2_1:
	s_waitcnt vmcnt(8)
	s_waitcnt lgkmcnt(0)
	s_barrier
	s_setprio 1
	s_waitcnt lgkmcnt(0)
	v_mfma_f32_16x16x32_bf16 v[62:65], v[164:167], v[196:199], v[62:65]
	v_mfma_f32_16x16x32_bf16 v[58:61], v[172:175], v[196:199], v[58:61]
	v_mfma_f32_16x16x32_bf16 v[54:57], v[164:167], v[204:207], v[54:57]
	v_mfma_f32_16x16x32_bf16 v[50:53], v[172:175], v[204:207], v[50:53]
	v_mfma_f32_16x16x32_bf16 v[46:49], v[164:167], v[236:239], v[46:49]
	v_mfma_f32_16x16x32_bf16 v[42:45], v[172:175], v[236:239], v[42:45]
	v_mfma_f32_16x16x32_bf16 v[38:41], v[164:167], v[244:247], v[38:41]
	v_mfma_f32_16x16x32_bf16 v[34:37], v[172:175], v[244:247], v[34:37]
	v_mfma_f32_16x16x32_bf16 v[62:65], v[168:171], v[200:203], v[62:65]
	v_mfma_f32_16x16x32_bf16 v[58:61], v[176:179], v[200:203], v[58:61]
	v_mfma_f32_16x16x32_bf16 v[54:57], v[168:171], v[220:223], v[54:57]
	v_mfma_f32_16x16x32_bf16 v[50:53], v[176:179], v[220:223], v[50:53]
	v_mfma_f32_16x16x32_bf16 v[46:49], v[168:171], v[240:243], v[46:49]
	v_mfma_f32_16x16x32_bf16 v[42:45], v[176:179], v[240:243], v[42:45]
	v_mfma_f32_16x16x32_bf16 v[38:41], v[168:171], v[248:251], v[38:41]
	v_mfma_f32_16x16x32_bf16 v[34:37], v[176:179], v[248:251], v[34:37]
	s_setprio 0
	s_setprio 1
	v_mfma_f32_16x16x32_bf16 v[30:33], v[180:183], v[196:199], v[30:33]
	v_mfma_f32_16x16x32_bf16 v[26:29], v[188:191], v[196:199], v[26:29]
	v_mfma_f32_16x16x32_bf16 v[22:25], v[180:183], v[204:207], v[22:25]
	v_mfma_f32_16x16x32_bf16 v[18:21], v[188:191], v[204:207], v[18:21]
	v_mfma_f32_16x16x32_bf16 v[14:17], v[180:183], v[236:239], v[14:17]
	v_mfma_f32_16x16x32_bf16 v[10:13], v[188:191], v[236:239], v[10:13]
	v_mfma_f32_16x16x32_bf16 v[6:9], v[180:183], v[244:247], v[6:9]
	v_mfma_f32_16x16x32_bf16 v[2:5], v[188:191], v[244:247], v[2:5]
	v_mfma_f32_16x16x32_bf16 v[30:33], v[184:187], v[200:203], v[30:33]
	v_mfma_f32_16x16x32_bf16 v[26:29], v[192:195], v[200:203], v[26:29]
	v_mfma_f32_16x16x32_bf16 v[22:25], v[184:187], v[220:223], v[22:25]
	v_mfma_f32_16x16x32_bf16 v[18:21], v[192:195], v[220:223], v[18:21]
	v_mfma_f32_16x16x32_bf16 v[14:17], v[184:187], v[240:243], v[14:17]
	v_mfma_f32_16x16x32_bf16 v[10:13], v[192:195], v[240:243], v[10:13]
	v_mfma_f32_16x16x32_bf16 v[6:9], v[184:187], v[248:251], v[6:9]
	v_mfma_f32_16x16x32_bf16 v[2:5], v[192:195], v[248:251], v[2:5]
	s_setprio 0
	s_barrier
	s_add_i32 s46, 0, 0x18000
	v_add_u32_e32 v163, s46, v159
	s_add_i32 s47, 0, 0x1c000
	ds_read_b128 v[164:167], v163
	ds_read_b128 v[168:171], v163 offset:1024
	ds_read_b128 v[172:175], v163 offset:2048
	ds_read_b128 v[176:179], v163 offset:3072
	v_add_u32_e32 v163, s47, v159
	ds_read_b128 v[180:183], v163
	ds_read_b128 v[184:187], v163 offset:1024
	ds_read_b128 v[188:191], v163 offset:2048
	ds_read_b128 v[192:195], v163 offset:3072
	s_add_u32 s24, s24, 0x40000
	s_addc_u32 s25, s25, 0
	s_mov_b32 m0, s34
	v_lshl_add_u64 v[230:231], s[24:25], 0, v[136:137]
	ds_read_b128 v[196:199], v162 offset:32768
	ds_read_b128 v[200:203], v162 offset:33792
	ds_read_b128 v[204:207], v162 offset:34816
	ds_read_b128 v[220:223], v162 offset:35840
	ds_read_b128 v[236:239], v162 offset:36864
	ds_read_b128 v[240:243], v162 offset:37888
	ds_read_b128 v[244:247], v162 offset:38912
	ds_read_b128 v[248:251], v162 offset:39936
	global_load_lds_dwordx4 v[230:231], off
	v_lshl_add_u64 v[230:231], s[24:25], 0, v[132:133]
	s_mov_b32 m0, s35
	s_nop 0
	global_load_lds_dwordx4 v[230:231], off
	s_waitcnt vmcnt(8)
	s_waitcnt lgkmcnt(0)
	s_barrier
	s_setprio 1
	s_waitcnt lgkmcnt(0)
	v_mfma_f32_16x16x32_bf16 v[126:129], v[164:167], v[196:199], v[126:129]
	v_mfma_f32_16x16x32_bf16 v[122:125], v[172:175], v[196:199], v[122:125]
	v_mfma_f32_16x16x32_bf16 v[118:121], v[164:167], v[204:207], v[118:121]
	v_mfma_f32_16x16x32_bf16 v[114:117], v[172:175], v[204:207], v[114:117]
	v_mfma_f32_16x16x32_bf16 v[110:113], v[164:167], v[236:239], v[110:113]
	v_mfma_f32_16x16x32_bf16 v[106:109], v[172:175], v[236:239], v[106:109]
	v_mfma_f32_16x16x32_bf16 v[102:105], v[164:167], v[244:247], v[102:105]
	v_mfma_f32_16x16x32_bf16 v[98:101], v[172:175], v[244:247], v[98:101]
	v_mfma_f32_16x16x32_bf16 v[126:129], v[168:171], v[200:203], v[126:129]
	v_mfma_f32_16x16x32_bf16 v[122:125], v[176:179], v[200:203], v[122:125]
	v_mfma_f32_16x16x32_bf16 v[118:121], v[168:171], v[220:223], v[118:121]
	v_mfma_f32_16x16x32_bf16 v[114:117], v[176:179], v[220:223], v[114:117]
	v_mfma_f32_16x16x32_bf16 v[110:113], v[168:171], v[240:243], v[110:113]
	v_mfma_f32_16x16x32_bf16 v[106:109], v[176:179], v[240:243], v[106:109]
	v_mfma_f32_16x16x32_bf16 v[102:105], v[168:171], v[248:251], v[102:105]
	v_mfma_f32_16x16x32_bf16 v[98:101], v[176:179], v[248:251], v[98:101]
	s_setprio 0
	s_setprio 1
	v_mfma_f32_16x16x32_bf16 v[94:97], v[180:183], v[196:199], v[94:97]
	v_mfma_f32_16x16x32_bf16 v[90:93], v[188:191], v[196:199], v[90:93]
	v_mfma_f32_16x16x32_bf16 v[86:89], v[180:183], v[204:207], v[86:89]
	v_mfma_f32_16x16x32_bf16 v[82:85], v[188:191], v[204:207], v[82:85]
	v_mfma_f32_16x16x32_bf16 v[78:81], v[180:183], v[236:239], v[78:81]
	v_mfma_f32_16x16x32_bf16 v[74:77], v[188:191], v[236:239], v[74:77]
	v_mfma_f32_16x16x32_bf16 v[70:73], v[180:183], v[244:247], v[70:73]
	v_mfma_f32_16x16x32_bf16 v[66:69], v[188:191], v[244:247], v[66:69]
	v_mfma_f32_16x16x32_bf16 v[94:97], v[184:187], v[200:203], v[94:97]
	v_mfma_f32_16x16x32_bf16 v[90:93], v[192:195], v[200:203], v[90:93]
	v_mfma_f32_16x16x32_bf16 v[86:89], v[184:187], v[220:223], v[86:89]
	v_mfma_f32_16x16x32_bf16 v[82:85], v[192:195], v[220:223], v[82:85]
	v_mfma_f32_16x16x32_bf16 v[78:81], v[184:187], v[240:243], v[78:81]
	v_mfma_f32_16x16x32_bf16 v[74:77], v[192:195], v[240:243], v[74:77]
	v_mfma_f32_16x16x32_bf16 v[70:73], v[184:187], v[248:251], v[70:73]
	v_mfma_f32_16x16x32_bf16 v[66:69], v[192:195], v[248:251], v[66:69]
	s_setprio 0
	s_barrier
	s_add_i32 s24, s46, s28
	v_lshl_add_u64 v[150:151], v[150:151], 0, s[96:97]
	s_mov_b32 m0, s24
	ds_read_b128 v[196:199], v162 offset:49152
	ds_read_b128 v[200:203], v162 offset:50176
	ds_read_b128 v[204:207], v162 offset:51200
	ds_read_b128 v[220:223], v162 offset:52224
	ds_read_b128 v[236:239], v162 offset:53248
	ds_read_b128 v[240:243], v162 offset:54272
	ds_read_b128 v[244:247], v162 offset:55296
	ds_read_b128 v[248:251], v162 offset:56320
	global_load_lds_dwordx4 v[150:151], off
	s_add_i32 m0, s24, 0x2000
	s_add_u32 s22, s22, 0x40080
	v_lshl_add_u64 v[150:151], v[208:209], 0, s[96:97]
	s_addc_u32 s23, s23, 0
	s_add_i32 s24, s47, s28
	global_load_lds_dwordx4 v[150:151], off
	v_lshl_add_u64 v[150:151], s[22:23], 0, v[134:135]
	s_mov_b32 m0, s24
	s_nop 0
	global_load_lds_dwordx4 v[150:151], off
	v_lshl_add_u64 v[150:151], s[22:23], 0, v[130:131]
	s_add_i32 m0, s24, 0x2000
	s_nop 0
	global_load_lds_dwordx4 v[150:151], off
	v_lshl_add_u64 v[150:151], v[224:225], 0, s[96:97]
	s_mov_b32 m0, s36
	s_nop 0
	global_load_lds_dwordx4 v[150:151], off
	v_lshl_add_u64 v[150:151], v[252:253], 0, s[96:97]
	s_mov_b32 m0, s37
	s_nop 0
	global_load_lds_dwordx4 v[150:151], off
	s_waitcnt vmcnt(8)
	s_waitcnt lgkmcnt(0)
	s_barrier
	s_setprio 1
	s_waitcnt lgkmcnt(0)
	v_mfma_f32_16x16x32_bf16 v[62:65], v[164:167], v[196:199], v[62:65]
	v_mfma_f32_16x16x32_bf16 v[58:61], v[172:175], v[196:199], v[58:61]
	v_mfma_f32_16x16x32_bf16 v[54:57], v[164:167], v[204:207], v[54:57]
	v_mfma_f32_16x16x32_bf16 v[50:53], v[172:175], v[204:207], v[50:53]
	v_mfma_f32_16x16x32_bf16 v[46:49], v[164:167], v[236:239], v[46:49]
	v_mfma_f32_16x16x32_bf16 v[42:45], v[172:175], v[236:239], v[42:45]
	v_mfma_f32_16x16x32_bf16 v[38:41], v[164:167], v[244:247], v[38:41]
	v_mfma_f32_16x16x32_bf16 v[34:37], v[172:175], v[244:247], v[34:37]
	v_mfma_f32_16x16x32_bf16 v[62:65], v[168:171], v[200:203], v[62:65]
	v_mfma_f32_16x16x32_bf16 v[58:61], v[176:179], v[200:203], v[58:61]
	v_mfma_f32_16x16x32_bf16 v[54:57], v[168:171], v[220:223], v[54:57]
	v_mfma_f32_16x16x32_bf16 v[50:53], v[176:179], v[220:223], v[50:53]
	v_mfma_f32_16x16x32_bf16 v[46:49], v[168:171], v[240:243], v[46:49]
	v_mfma_f32_16x16x32_bf16 v[42:45], v[176:179], v[240:243], v[42:45]
	v_mfma_f32_16x16x32_bf16 v[38:41], v[168:171], v[248:251], v[38:41]
	v_mfma_f32_16x16x32_bf16 v[34:37], v[176:179], v[248:251], v[34:37]
	s_setprio 0
	s_setprio 1
	v_mfma_f32_16x16x32_bf16 v[30:33], v[180:183], v[196:199], v[30:33]
	v_mfma_f32_16x16x32_bf16 v[26:29], v[188:191], v[196:199], v[26:29]
	v_mfma_f32_16x16x32_bf16 v[22:25], v[180:183], v[204:207], v[22:25]
	v_mfma_f32_16x16x32_bf16 v[18:21], v[188:191], v[204:207], v[18:21]
	v_mfma_f32_16x16x32_bf16 v[14:17], v[180:183], v[236:239], v[14:17]
	v_mfma_f32_16x16x32_bf16 v[10:13], v[188:191], v[236:239], v[10:13]
	v_mfma_f32_16x16x32_bf16 v[6:9], v[180:183], v[244:247], v[6:9]
	v_mfma_f32_16x16x32_bf16 v[2:5], v[188:191], v[244:247], v[2:5]
	v_mfma_f32_16x16x32_bf16 v[30:33], v[184:187], v[200:203], v[30:33]
	v_mfma_f32_16x16x32_bf16 v[26:29], v[192:195], v[200:203], v[26:29]
	v_mfma_f32_16x16x32_bf16 v[22:25], v[184:187], v[220:223], v[22:25]
	v_mfma_f32_16x16x32_bf16 v[18:21], v[192:195], v[220:223], v[18:21]
	v_mfma_f32_16x16x32_bf16 v[14:17], v[184:187], v[240:243], v[14:17]
	v_mfma_f32_16x16x32_bf16 v[10:13], v[192:195], v[240:243], v[10:13]
	v_mfma_f32_16x16x32_bf16 v[6:9], v[184:187], v[248:251], v[6:9]
	v_mfma_f32_16x16x32_bf16 v[2:5], v[192:195], v[248:251], v[2:5]
	s_setprio 0
	s_barrier
	s_add_i32 s45, s45, 2
	s_add_u32 s43, s43, 0x100
	s_addc_u32 s44, s44, 0
	s_add_u32 s20, s20, 0x100
	s_addc_u32 s21, s21, 0
	s_cmp_gt_u32 s45, 13
	s_cbranch_scc0 .LBB0_640
	s_and_b64 vcc, exec, s[8:9]
	s_cbranch_vccz .LBB0_643
	s_barrier
